# GQA meta-key tile fast path (keys 0..15 only) for units away from the sequence start; B/C units alternate per workgroup
# baseline (speedup 1.0000x reference)
; #define RUN_BC(j) do { const int u_ = (j) >> 1, k_ = u_ / (NBATCH * 65); if ((j) & 1) { attn_unit<2>(P, u_, (LAS char*)lds, k_ != keyC); keyC = k_; } else { attn_unit<1>(P, u_, (LAS char*)lds, k_ != keyB); keyB = k_; } } while (0)
; __global__ void __launch_bounds__(512, 2) fwd_kernel(Args a) {
;     ...
;           if (G == 256) {
;               if (wg < 64) { for (int j = (wg & 7) * 8 + (wg >> 3); j < NLOW; j += 64) RUN_BC(j); }
;               else { for (int j = NLOW + (wg & 7) * 24 + ((wg - 64) >> 3); j < NBC; j += 192) RUN_BC(j); }
.LBB0_1004:
	s_add_i32 s0, s63, 0xc0
	s_xor_b32 s0, s0, 1
	s_cmpk_gt_u32 s63, 0xf7f
	s_mov_b32 s63, s0
	s_cbranch_scc1 .LBB0_1186

; #define LAS __attribute__((address_space(3)))
; __device__ __forceinline__ int crow(int r, int hi) { return (r & 3) + 8 * (r >> 2) + 4 * hi; }
; template <int MODE> __device__ __forceinline__ void attn_unit(const AttnP& P, int u, LAS char* lds, bool fill) {
;     ...
;         for (int ds = 0; ds < 4; ++ds) {
;             const bf16x8 k0 = *(const LAS bf16x8*)(kb + ds * 32);
;             const bf16x8 k1 = *(const LAS bf16x8*)(kb + 32 * APITCH + ds * 32);
;             p0 = __builtin_amdgcn_mfma_f32_32x32x16_bf16(k0, qr[ds], p0, 0, 0, 0);
;             p1 = __builtin_amdgcn_mfma_f32_32x32x16_bf16(k1, qr[ds], p1, 0, 0, 0);
;         }
;         if (MODE == 0) {
;             const bool farl = (tok0 + 63 + 128 <= qtok0), farr = (tok0 - (qtok0 + 31) >= 128) && (tok0 + 64 <= LT);
;             if (farl || farr) { const float cb = farl ? mytab[0] : mytab[256];
; #pragma unroll
;                 for (int r = 0; r < 16; ++r) { p0[r] += cb; p1[r] += cb; } }
;             else {
; #pragma unroll
;                 for (int r = 0; r < 16; ++r) { const int tk0 = tok0 + crow(r, hi), tk1 = tk0 + 32;
;                     int i0 = tk0 - tq + 128; i0 = i0 < 0 ? 0 : (i0 > 256 ? 256 : i0); int i1 = tk1 - tq + 128; i1 = i1 < 0 ? 0 : (i1 > 256 ? 256 : i1);
;                     p0[r] = tk0 < LT ? p0[r] + mytab[i0] : NEGV; p1[r] = tk1 < LT ? p1[r] + mytab[i1] : NEGV; } }
;         } else if (MODE == 2) {
;           if (tok0 >= NMETA && tok0 + 64 <= LT) {
;             const LAS float* t2 = mytab2 + (tok0 - tq + 191 + 4 * hi);
; #pragma unroll
;             for (int r = 0; r < 16; ++r) { p0[r] += t2[(r & 3) + 8 * (r >> 2)]; p1[r] += t2[(r & 3) + 8 * (r >> 2) + 32]; }
;           } else
; #pragma unroll
;             for (int r = 0; r < 16; ++r) { const int tk0 = tok0 + crow(r, hi), tk1 = tk0 + 32; const int r0 = tk0 - tq, r1 = tk1 - tq;
;                 int i0 = r0 + 128; i0 = i0 < 0 ? 0 : (i0 > 256 ? 256 : i0); int i1 = r1 + 128; i1 = i1 < 0 ? 0 : (i1 > 256 ? 256 : i1);
;                 const bool v0 = (tk0 < NMETA || (r0 >= -128 && r0 <= 128)) && tk0 < LT, v1 = (tk1 < NMETA || (r1 >= -128 && r1 <= 128)) && tk1 < LT;
;                 p0[r] = v0 ? p0[r] + mytab[i0] : NEGV; p1[r] = v1 ? p1[r] + mytab[i1] : NEGV; }
.LBB0_1028:
	s_and_b64 vcc, exec, s[46:47]
	s_cbranch_vccnz .Lgqa1_t0fast
	s_mul_i32 s15, s34, 0x404
	s_add_i32 s31, s15, 0
	s_movk_i32 s15, 0x90
	v_mad_u32_u24 v3, v66, s15, 0
	v_lshlrev_b32_e32 v68, 4, v2
	v_add_u32_e32 v127, v3, v68
	v_lshlrev_b32_e32 v67, 2, v2
	ds_read_b128 v[18:21], v127 offset:4608
	ds_read_b128 v[2:5], v127
	ds_read_b128 v[36:39], v127 offset:32
	s_waitcnt lgkmcnt(1)
	v_mfma_f32_32x32x16_bf16 v[2:17], v[2:5], v[98:101], 0
	ds_read_b128 v[40:43], v127 offset:4640
	s_add_i32 s31, s31, 0x1b000
	v_mfma_f32_32x32x16_bf16 v[18:33], v[18:21], v[98:101], 0
	s_waitcnt lgkmcnt(1)
	v_mfma_f32_32x32x16_bf16 v[2:17], v[36:39], v[102:105], v[2:17]
	s_waitcnt lgkmcnt(0)
	v_mfma_f32_32x32x16_bf16 v[18:33], v[40:43], v[102:105], v[18:33]
	ds_read_b128 v[36:39], v127 offset:64
	ds_read_b128 v[40:43], v127 offset:4672
	s_waitcnt lgkmcnt(1)
	v_mfma_f32_32x32x16_bf16 v[2:17], v[36:39], v[106:109], v[2:17]
	s_waitcnt lgkmcnt(0)
	v_mfma_f32_32x32x16_bf16 v[18:33], v[40:43], v[106:109], v[18:33]
	ds_read_b128 v[36:39], v127 offset:96
	ds_read_b128 v[40:43], v127 offset:4704
	s_waitcnt lgkmcnt(1)
	v_mfma_f32_32x32x16_bf16 v[2:17], v[36:39], v[110:113], v[2:17]
	v_sub_u32_e32 v36, v67, v125
	v_add_u32_e32 v35, 0xa0, v36
	v_cmp_gt_u32_e32 vcc, s6, v35
	v_med3_i32 v35, v36, s87, v240
	v_lshl_add_u32 v35, v35, 2, s31
	ds_read_b32 v37, v35 offset:512
	v_mov_b32_e32 v35, 0xf149f2ca
	s_waitcnt lgkmcnt(1)
	v_mfma_f32_32x32x16_bf16 v[18:33], v[40:43], v[110:113], v[18:33]
	v_lshl_add_u32 v39, v36, 2, s31
	v_mov_b32_e32 v36, 0xf149f2ca
	s_and_saveexec_b64 s[28:29], vcc
	s_cbranch_execz .LBB0_1030
	ds_read_b32 v36, v39 offset:640
	s_waitcnt lgkmcnt(0)
	s_nop 5
	v_add_f32_e32 v36, v18, v36

; #define LAS __attribute__((address_space(3)))
; template <int MODE> __device__ __forceinline__ void attn_unit(const AttnP& P, int u, LAS char* lds, bool fill) {
;     ...
;             for (int r = 0; r < 16; ++r) { const int tk0 = tok0 + crow(r, hi), tk1 = tk0 + 32; const int r0 = tk0 - tq, r1 = tk1 - tq;
;                 int i0 = r0 + 128; i0 = i0 < 0 ? 0 : (i0 > 256 ? 256 : i0); int i1 = r1 + 128; i1 = i1 < 0 ? 0 : (i1 > 256 ? 256 : i1);
;                 const bool v0 = (tk0 < NMETA || (r0 >= -128 && r0 <= 128)) && tk0 < LT, v1 = (tk1 < NMETA || (r1 >= -128 && r1 <= 128)) && tk1 < LT;
;                 p0[r] = v0 ? p0[r] + mytab[i0] : NEGV; p1[r] = v1 ? p1[r] + mytab[i1] : NEGV; }
;         } else {
;             if (t == 0) {
; #pragma unroll
;                 for (int r = 0; r < 16; ++r) { const int k0 = crow(r, hi); p0[r] = k0 < NMETA ? p0[r] : NEGV; p1[r] = NEGV; }
;             } else {
;                 const int roff = (rs_ + t - 1) - x2 + 7;
;                 const LAS float* rt = metaunit ? tab + 4 * 593 + 4 * hi : mytab + roff * 31 + 15 - ccol + 4 * hi;
; #pragma unroll
;                 for (int r = 0; r < 16; ++r) { p0[r] = p0[r] + rt[(r & 3) + 8 * (r >> 2)] + ng0[r]; p1[r] = p1[r] + rt[(r & 3) + 8 * (r >> 2) + 32] + ng1[r]; }
;             }
;         }
;         float mx = p0[0];
; #pragma unroll
;         for (int r = 1; r < 16; ++r) mx = fmaxf(mx, p0[r]);
; #pragma unroll
;         for (int r = 0; r < 16; ++r) mx = fmaxf(mx, p1[r]);
;         { const auto rr = __builtin_amdgcn_permlane32_swap(__float_as_uint(mx), __float_as_uint(mx), false, false); mx = fmaxf(__uint_as_float(rr[0]), __uint_as_float(rr[1])); }
;         if (__any(mx > mrun + 8.0f)) {
;             const float mnew = fmaxf(mrun, mx); const float f = __builtin_amdgcn_exp2f(mrun - mnew); mrun = mnew; lrun *= f;
; #pragma unroll
;             for (int d = 0; d < ND; ++d)
; #pragma unroll
;                 for (int r = 0; r < 16; ++r) o[d][r] *= f;
;         }
;         float sacc = 0.f;
; #pragma unroll
;         for (int r = 0; r < 16; ++r) { p0[r] = __builtin_amdgcn_exp2f(p0[r] - mrun); p1[r] = __builtin_amdgcn_exp2f(p1[r] - mrun); sacc += p0[r] + p1[r]; }
;         lrun += sacc;
;         bf16x8 pf[4];
;         { u32x4 a;
;           a.x = cvtpk(p0[0], p0[1]); a.y = cvtpk(p0[2], p0[3]); a.z = cvtpk(p0[4], p0[5]); a.w = cvtpk(p0[6], p0[7]); pf[0] = __builtin_bit_cast(bf16x8, a);
.LBB0_1076:
	s_or_b64 exec, exec, s[28:29]
	v_lshrrev_b32_e32 v17, 2, v34
	v_and_or_b32 v17, v17, 3, v67
	v_mul_u32_u24_e32 v33, 0x90, v17
	s_waitcnt lgkmcnt(0)
	v_add_f32_e32 v17, v9, v45
	v_add_f32_e32 v39, v8, v44
	v_lshlrev_b32_e32 v8, 1, v34
	v_lshlrev_b32_e32 v9, 3, v34
	v_add_f32_e32 v3, v3, v38
	v_add_f32_e32 v2, v2, v37
	v_and_b32_e32 v8, 32, v8
	v_and_b32_e32 v9, 24, v9
	v_add_f32_e32 v5, v5, v41
	v_add_f32_e32 v4, v4, v40
	v_add3_u32 v37, 0, v8, v9
	v_max_f32_e32 v8, v2, v3
	v_add_f32_e32 v7, v7, v43
	v_add_f32_e32 v6, v6, v42
	v_max3_f32 v8, v8, v4, v5
	v_max3_f32 v8, v8, v6, v7
	v_max3_f32 v8, v8, v39, v17
	v_max3_f32 v8, v8, v24, v10
	v_max3_f32 v8, v8, v11, v28
	v_max3_f32 v8, v8, v13, v30
	v_max3_f32 v8, v8, v15, v32
	v_max3_f32 v8, v8, v36, v35
	v_max3_f32 v8, v8, v19, v18
	v_max3_f32 v8, v8, v21, v20
	v_max3_f32 v8, v8, v23, v22
	v_max3_f32 v8, v8, v25, v26
	v_max3_f32 v8, v8, v27, v12
	v_max3_f32 v8, v8, v29, v14
	v_max3_f32 v8, v8, v31, v16
	v_mov_b32_e32 v9, v8
	s_nop 1
	v_permlane32_swap_b32_e32 v8, v9
	v_max_f32_e32 v9, v9, v9
	v_max_f32_e32 v8, v8, v8
	v_max_f32_e32 v8, v8, v9
	s_mov_b32 s15, 0xf149f2ca
	v_cmp_lt_f32_e32 vcc, s15, v8
	s_cmp_eq_u64 vcc, 0
	s_cselect_b64 vcc, -1, 0
	v_max_f32_e32 v8, 0xf149f2ca, v8
	v_cndmask_b32_e32 v128, v8, v242, vcc
	v_sub_f32_e32 v2, v2, v128
	v_exp_f32_e32 v38, v2
	v_sub_f32_e32 v2, v36, v128
	v_exp_f32_e32 v36, v2
	v_sub_f32_e32 v2, v3, v128
	v_exp_f32_e32 v40, v2
	v_sub_f32_e32 v2, v35, v128
	v_exp_f32_e32 v35, v2
	v_sub_f32_e32 v2, v4, v128
	v_exp_f32_e32 v41, v2
	v_sub_f32_e32 v2, v19, v128
	v_exp_f32_e32 v42, v2
	v_sub_f32_e32 v2, v5, v128
	v_exp_f32_e32 v43, v2
	v_sub_f32_e32 v2, v18, v128
	v_exp_f32_e32 v44, v2
	v_sub_f32_e32 v2, v6, v128
	v_exp_f32_e32 v3, v2
	v_sub_f32_e32 v2, v21, v128
	v_exp_f32_e32 v5, v2
	v_sub_f32_e32 v2, v7, v128
	v_sub_f32_e32 v4, v20, v128
	v_sub_f32_e32 v9, 0xf149f2ca, v8
	v_exp_f32_e32 v2, v2
	v_exp_f32_e32 v4, v4
	v_exp_f32_e32 v9, v9
	v_add_u32_e32 v129, v37, v33
	v_pk_mov_b32 v[6:7], v[2:3], v[2:3] op_sel:[1,0]
	v_pk_add_f32 v[54:55], v[2:3], v[4:5]
	v_sub_f32_e32 v2, v39, v128
	v_mul_f32_e32 v9, 0, v9
	v_exp_f32_e32 v3, v2
	v_sub_f32_e32 v2, v23, v128
	v_cndmask_b32_e64 v34, v9, 0, vcc
	v_pk_mov_b32 v[8:9], v[4:5], v[4:5] op_sel:[1,0]
	v_exp_f32_e32 v5, v2
	v_sub_f32_e32 v2, v17, v128
	v_sub_f32_e32 v4, v22, v128
	v_exp_f32_e32 v2, v2
	v_exp_f32_e32 v4, v4
	v_add_f32_e32 v69, v38, v36
	v_add_f32_e32 v70, v40, v35
	v_pk_mov_b32 v[18:19], v[2:3], v[2:3] op_sel:[1,0]
	v_pk_add_f32 v[56:57], v[2:3], v[4:5]
	v_sub_f32_e32 v2, v24, v128
	v_exp_f32_e32 v3, v2
	v_sub_f32_e32 v2, v25, v128
	v_pk_mov_b32 v[20:21], v[4:5], v[4:5] op_sel:[1,0]
	v_exp_f32_e32 v5, v2
	v_sub_f32_e32 v2, v10, v128
	v_sub_f32_e32 v4, v26, v128
	v_exp_f32_e32 v2, v2
	v_exp_f32_e32 v4, v4
	v_add_f32_e32 v71, v41, v42
	v_add_f32_e32 v72, v43, v44
	v_pk_mov_b32 v[22:23], v[2:3], v[2:3] op_sel:[1,0]
	v_pk_add_f32 v[58:59], v[2:3], v[4:5]
	v_sub_f32_e32 v2, v11, v128
	v_exp_f32_e32 v3, v2
	v_sub_f32_e32 v2, v27, v128
	v_pk_mov_b32 v[24:25], v[4:5], v[4:5] op_sel:[1,0]
	v_exp_f32_e32 v5, v2
	v_sub_f32_e32 v2, v28, v128
	v_sub_f32_e32 v4, v12, v128
	v_exp_f32_e32 v2, v2
	v_exp_f32_e32 v4, v4
	v_cvt_pk_bf16_f32 v74, v38, v40
	v_cvt_pk_bf16_f32 v75, v41, v43
	v_pk_mov_b32 v[10:11], v[2:3], v[2:3] op_sel:[1,0]
	v_pk_add_f32 v[60:61], v[2:3], v[4:5]
	v_sub_f32_e32 v2, v13, v128
	v_exp_f32_e32 v3, v2
	v_sub_f32_e32 v2, v29, v128
	v_pk_mov_b32 v[26:27], v[4:5], v[4:5] op_sel:[1,0]
	v_exp_f32_e32 v5, v2
	v_sub_f32_e32 v2, v30, v128
	v_sub_f32_e32 v4, v14, v128
	v_exp_f32_e32 v2, v2
	v_exp_f32_e32 v4, v4
	v_cvt_pk_bf16_f32 v76, v6, v7
	v_cvt_pk_bf16_f32 v77, v18, v19
	v_pk_mov_b32 v[12:13], v[2:3], v[2:3] op_sel:[1,0]
	v_pk_add_f32 v[62:63], v[2:3], v[4:5]
	v_sub_f32_e32 v2, v15, v128
	v_exp_f32_e32 v3, v2
	v_sub_f32_e32 v2, v31, v128
	v_pk_mov_b32 v[28:29], v[4:5], v[4:5] op_sel:[1,0]
	v_exp_f32_e32 v5, v2
	v_sub_f32_e32 v2, v32, v128
	v_sub_f32_e32 v4, v16, v128
	v_exp_f32_e32 v2, v2
	v_exp_f32_e32 v4, v4
	v_cvt_pk_bf16_f32 v82, v36, v35
	v_cvt_pk_bf16_f32 v83, v42, v44
	v_pk_mov_b32 v[14:15], v[2:3], v[2:3] op_sel:[1,0]
	v_pk_mov_b32 v[16:17], v[4:5], v[4:5] op_sel:[1,0]
	v_pk_add_f32 v[64:65], v[2:3], v[4:5]
	ds_read_b64_tr_b16 v[2:3], v129 offset:9216
	ds_read_b64_tr_b16 v[4:5], v129 offset:10368
	v_mov_b32_e32 v35, v34
	v_mov_b32_e32 v36, v34
	v_mov_b32_e32 v37, v34
	v_mov_b32_e32 v38, v34
	v_mov_b32_e32 v39, v34
	v_mov_b32_e32 v40, v34
	v_mov_b32_e32 v41, v34
	v_mov_b32_e32 v42, v34
	v_mov_b32_e32 v43, v34
	v_mov_b32_e32 v44, v34
	v_mov_b32_e32 v45, v34
	v_mov_b32_e32 v46, v34
	v_mov_b32_e32 v47, v34
	v_mov_b32_e32 v48, v34
	v_mov_b32_e32 v49, v34
	v_cvt_pk_bf16_f32 v78, v22, v23
	v_cvt_pk_bf16_f32 v85, v20, v21
	v_cvt_pk_bf16_f32 v50, v24, v25
	v_cvt_pk_bf16_f32 v51, v26, v27
	v_cvt_pk_bf16_f32 v52, v28, v29
	s_waitcnt lgkmcnt(0)
	v_mfma_f32_32x32x16_bf16 v[18:33], v[2:5], v[74:77], v[34:49]
	ds_read_b64_tr_b16 v[2:3], v129 offset:11520
	ds_read_b64_tr_b16 v[4:5], v129 offset:12672
	v_cvt_pk_bf16_f32 v79, v10, v11
	v_cvt_pk_bf16_f32 v80, v12, v13
	v_cvt_pk_bf16_f32 v81, v14, v15
	v_cvt_pk_bf16_f32 v84, v8, v9
	v_cvt_pk_bf16_f32 v53, v16, v17
	s_andn2_b64 vcc, exec, s[0:1]
	s_waitcnt lgkmcnt(0)
; template <int MODE> __device__ __forceinline__ void attn_unit(const AttnP& P, int u, LAS char* lds, bool fill) {
;     ...
;         for (int ds = 0; ds < 4; ++ds) {
;     ...
;         float mx = p0[0];
; #pragma unroll
;         for (int r = 1; r < 16; ++r) mx = fmaxf(mx, p0[r]);
; #pragma unroll
;         for (int r = 0; r < 16; ++r) mx = fmaxf(mx, p1[r]);
;         { const auto rr = __builtin_amdgcn_permlane32_swap(__float_as_uint(mx), __float_as_uint(mx), false, false); mx = fmaxf(__uint_as_float(rr[0]), __uint_as_float(rr[1])); }
;         if (__any(mx > mrun + 8.0f)) {
;             const float mnew = fmaxf(mrun, mx); const float f = __builtin_amdgcn_exp2f(mrun - mnew); mrun = mnew; lrun *= f;
; #pragma unroll
;             for (int d = 0; d < ND; ++d)
; #pragma unroll
;                 for (int r = 0; r < 16; ++r) o[d][r] *= f;
;         }
;         float sacc = 0.f;
; #pragma unroll
;         for (int r = 0; r < 16; ++r) { p0[r] = __builtin_amdgcn_exp2f(p0[r] - mrun); p1[r] = __builtin_amdgcn_exp2f(p1[r] - mrun); sacc += p0[r] + p1[r]; }
;         lrun += sacc;
;         bf16x8 pf[4];
;         { u32x4 a;
;           a.x = cvtpk(p0[0], p0[1]); a.y = cvtpk(p0[2], p0[3]); a.z = cvtpk(p0[4], p0[5]); a.w = cvtpk(p0[6], p0[7]); pf[0] = __builtin_bit_cast(bf16x8, a);
;           a.x = cvtpk(p0[8], p0[9]); a.y = cvtpk(p0[10], p0[11]); a.z = cvtpk(p0[12], p0[13]); a.w = cvtpk(p0[14], p0[15]); pf[1] = __builtin_bit_cast(bf16x8, a);
;           a.x = cvtpk(p1[0], p1[1]); a.y = cvtpk(p1[2], p1[3]); a.z = cvtpk(p1[4], p1[5]); a.w = cvtpk(p1[6], p1[7]); pf[2] = __builtin_bit_cast(bf16x8, a);
;           a.x = cvtpk(p1[8], p1[9]); a.y = cvtpk(p1[10], p1[11]); a.z = cvtpk(p1[12], p1[13]); a.w = cvtpk(p1[14], p1[15]); pf[3] = __builtin_bit_cast(bf16x8, a); }
; #pragma unroll
;         for (int d = 0; d < ND; ++d) {
;             const int vslot = MODE == 0 ? 2 + (d >> 1) : MODE == 1 ? kslot + 1 : 1;
;             const LAS char* vb = lds + vslot * ASLOT + vrow * APITCH + (d & 1) * 64 + vcolb;
; #pragma unroll
;             for (int ks = 0; ks < 4; ++ks) {
;                 const s16x4 vl = vtr(vb + (16 * ks) * APITCH), vh = vtr(vb + (16 * ks + 8) * APITCH);
;                 const bf16x8 vf = (bf16x8){vl[0], vl[1], vl[2], vl[3], vh[0], vh[1], vh[2], vh[3]};
;                 o[d] = __builtin_amdgcn_mfma_f32_32x32x16_bf16(vf, pf[ks], o[d], 0, 0, 0);
;             }
;         }
	v_mfma_f32_32x32x16_bf16 v[18:33], v[2:5], v[78:81], v[18:33]
	ds_read_b64_tr_b16 v[2:3], v129 offset:13824
	ds_read_b64_tr_b16 v[4:5], v129 offset:14976
	s_waitcnt lgkmcnt(0)
	v_mfma_f32_32x32x16_bf16 v[18:33], v[2:5], v[82:85], v[18:33]
	ds_read_b64_tr_b16 v[2:3], v129 offset:16128
	ds_read_b64_tr_b16 v[4:5], v129 offset:17280
	ds_read_b64_tr_b16 v[86:87], v129 offset:9280
	ds_read_b64_tr_b16 v[88:89], v129 offset:10432
	s_waitcnt lgkmcnt(2)
	v_mfma_f32_32x32x16_bf16 v[18:33], v[2:5], v[50:53], v[18:33]
	v_mov_b64_e32 v[2:3], v[34:35]
	v_mov_b64_e32 v[4:5], v[36:37]
	v_mov_b64_e32 v[6:7], v[38:39]
	v_mov_b64_e32 v[8:9], v[40:41]
	v_mov_b64_e32 v[10:11], v[42:43]
	v_mov_b64_e32 v[12:13], v[44:45]
	v_mov_b64_e32 v[14:15], v[46:47]
	v_mov_b64_e32 v[16:17], v[48:49]
	ds_read_b64_tr_b16 v[36:37], v129 offset:11584
	ds_read_b64_tr_b16 v[38:39], v129 offset:12736
	s_waitcnt lgkmcnt(2)
	v_mfma_f32_32x32x16_bf16 v[2:17], v[86:89], v[74:77], v[2:17]
	v_add_f32_e32 v35, 0, v69
	v_add_f32_e32 v35, v70, v35
	v_add_f32_e32 v35, v71, v35
	v_add_f32_e32 v35, v72, v35
	v_add_f32_e32 v35, v55, v35
	v_add_f32_e32 v35, v54, v35
	v_add_f32_e32 v35, v57, v35
	s_waitcnt lgkmcnt(0)
	v_mfma_f32_32x32x16_bf16 v[2:17], v[36:39], v[78:81], v[2:17]
	ds_read_b64_tr_b16 v[36:37], v129 offset:13888
	ds_read_b64_tr_b16 v[38:39], v129 offset:15040
	v_add_f32_e32 v35, v56, v35
	v_add_f32_e32 v35, v59, v35
	v_add_f32_e32 v35, v58, v35
	v_add_f32_e32 v35, v61, v35
	v_add_f32_e32 v35, v60, v35
	v_add_f32_e32 v35, v63, v35
	s_waitcnt lgkmcnt(0)
	v_mfma_f32_32x32x16_bf16 v[2:17], v[36:39], v[82:85], v[2:17]
	ds_read_b64_tr_b16 v[36:37], v129 offset:16192
	ds_read_b64_tr_b16 v[38:39], v129 offset:17344
	v_add_f32_e32 v35, v62, v35
	v_add_f32_e32 v35, v65, v35
	v_add_f32_e32 v35, v64, v35
	v_add_f32_e32 v130, v34, v35
	s_waitcnt lgkmcnt(0)
	v_mfma_f32_32x32x16_bf16 v[2:17], v[36:39], v[50:53], v[2:17]
	s_cbranch_vccnz .LBB0_1152
	s_branch .Lgqa1_t0done
.Lgqa1_t0fast:
	s_mul_i32 s15, s34, 0x404
	s_add_i32 s31, s15, 0x1b000
	s_movk_i32 s15, 0x90
	v_mad_u32_u24 v40, v66, s15, 0
	v_lshlrev_b32_e32 v68, 4, v2
	v_lshlrev_b32_e32 v67, 2, v2
	v_add_u32_e32 v127, v40, v68
	v_lshrrev_b32_e32 v41, 2, v34
	v_and_or_b32 v41, v41, 3, v67
	v_mul_u32_u24_e32 v42, 0x90, v41
	v_lshlrev_b32_e32 v43, 1, v34
	v_lshlrev_b32_e32 v44, 3, v34
	v_and_b32_e32 v43, 32, v43
	v_and_b32_e32 v44, 24, v44
	v_add3_u32 v45, 0, v43, v44
	v_add_u32_e32 v129, v45, v42
	v_mov_b32_e32 v88, s31
	ds_read_b32 v88, v88
	ds_read_b128 v[50:53], v127
	ds_read_b128 v[54:57], v127 offset:32
	ds_read_b128 v[58:61], v127 offset:64
	ds_read_b128 v[62:65], v127 offset:96
	ds_read_b64_tr_b16 v[84:85], v129 offset:9216
	ds_read_b64_tr_b16 v[86:87], v129 offset:10368
	ds_read_b64_tr_b16 v[74:75], v129 offset:9280
	ds_read_b64_tr_b16 v[76:77], v129 offset:10432
	s_waitcnt lgkmcnt(7)
	v_mfma_f32_32x32x16_bf16 v[34:49], v[50:53], v[98:101], 0
	s_waitcnt lgkmcnt(6)
	v_mfma_f32_32x32x16_bf16 v[34:49], v[54:57], v[102:105], v[34:49]
	s_waitcnt lgkmcnt(5)
	v_mfma_f32_32x32x16_bf16 v[34:49], v[58:61], v[106:109], v[34:49]
	s_waitcnt lgkmcnt(4)
	v_mfma_f32_32x32x16_bf16 v[34:49], v[62:65], v[110:113], v[34:49]
	s_nop 11
	v_add_f32_e32 v34, v34, v88
	v_add_f32_e32 v35, v35, v88
	v_add_f32_e32 v36, v36, v88
	v_add_f32_e32 v37, v37, v88
	v_add_f32_e32 v38, v38, v88
	v_add_f32_e32 v39, v39, v88
	v_add_f32_e32 v40, v40, v88
	v_add_f32_e32 v41, v41, v88
	v_max3_f32 v47, v34, v35, v36
	v_max3_f32 v47, v47, v37, v38
	v_max3_f32 v47, v47, v39, v40
	v_max_f32_e32 v47, v47, v41
	v_mov_b32_e32 v48, v47
	s_nop 1
	v_permlane32_swap_b32_e32 v47, v48
	v_max_f32_e32 v47, v47, v48
	v_max_f32_e32 v128, 0xf149f2ca, v47
	v_sub_f32_e32 v34, v34, v128
	v_sub_f32_e32 v35, v35, v128
	v_sub_f32_e32 v36, v36, v128
	v_sub_f32_e32 v37, v37, v128
	v_sub_f32_e32 v38, v38, v128
	v_sub_f32_e32 v39, v39, v128
	v_sub_f32_e32 v40, v40, v128
	v_sub_f32_e32 v41, v41, v128
	v_exp_f32_e32 v34, v34
	v_exp_f32_e32 v35, v35
	v_exp_f32_e32 v36, v36
	v_exp_f32_e32 v37, v37
	v_exp_f32_e32 v38, v38
	v_exp_f32_e32 v39, v39
	v_exp_f32_e32 v40, v40
	v_exp_f32_e32 v41, v41
	v_add_f32_e32 v130, v34, v35
	v_add_f32_e32 v130, v130, v36
	v_add_f32_e32 v130, v130, v37
	v_add_f32_e32 v130, v130, v38
	v_add_f32_e32 v130, v130, v39
	v_add_f32_e32 v130, v130, v40
	v_add_f32_e32 v130, v130, v41
	v_cvt_pk_bf16_f32 v80, v34, v35
	v_cvt_pk_bf16_f32 v81, v36, v37
	v_cvt_pk_bf16_f32 v82, v38, v39
	v_cvt_pk_bf16_f32 v83, v40, v41
	s_nop 1
	s_waitcnt lgkmcnt(0)
	v_mfma_f32_32x32x16_bf16 v[18:33], v[84:87], v[80:83], 0
	v_mfma_f32_32x32x16_bf16 v[2:17], v[74:77], v[80:83], 0
	s_andn2_b64 vcc, exec, s[0:1]
	s_cbranch_vccnz .LBB0_1152
.Lgqa1_t0done:
	s_add_i32 s15, s44, 0xffffff40
	s_and_b64 s[0:1], s[46:47], exec
	s_cselect_b32 s35, s15, 0
	s_mul_i32 s16, s34, 0x600
	s_lshl_b32 s0, s35, 2
	s_add_i32 s0, s0, s16
	v_add_u32_e32 v34, s0, v68
	v_add_lshl_u32 v35, s39, v66, 2
	s_lshl_b32 s0, s14, 1
	v_sub_u32_e32 v34, v34, v35
	s_and_b32 s0, s0, 0x80
	v_subrev_u32_e32 v34, s0, v34
	v_readlane_b32 s0, v255, 24
	s_add_i32 s43, s43, s39
	v_add_u32_e32 v132, s35, v67
	v_add_u32_e32 v131, s0, v34
	v_add_u32_e32 v34, s43, v66
	s_mov_b32 s34, 0
	s_mov_b32 s38, 1
	s_sub_i32 s14, s44, 64
	v_sub_u32_e32 v133, v132, v34
	s_branch .LBB0_1079

; #define RUN_BC(j) do { const int u_ = (j) >> 1, k_ = u_ / (NBATCH * 65); if ((j) & 1) { attn_unit<2>(P, u_, (LAS char*)lds, k_ != keyC); keyC = k_; } else { attn_unit<1>(P, u_, (LAS char*)lds, k_ != keyB); keyB = k_; } } while (0)
; __global__ void __launch_bounds__(512, 2) fwd_kernel(Args a) {
;     ...
;               if (wg < 64) { for (int j = (wg & 7) * 8 + (wg >> 3); j < NLOW; j += 64) RUN_BC(j); }
.LBB0_1191:
	s_add_i32 s0, s27, 64
	s_xor_b32 s0, s0, 1
	s_cmpk_gt_i32 s27, 0x2bf
	s_mov_b32 s27, s0
	s_cbranch_scc1 .LBB0_1373

; #define LAS __attribute__((address_space(3)))
; __device__ __forceinline__ int crow(int r, int hi) { return (r & 3) + 8 * (r >> 2) + 4 * hi; }
; template <int MODE> __device__ __forceinline__ void attn_unit(const AttnP& P, int u, LAS char* lds, bool fill) {
;     ...
;         for (int ds = 0; ds < 4; ++ds) {
;             const bf16x8 k0 = *(const LAS bf16x8*)(kb + ds * 32);
;             const bf16x8 k1 = *(const LAS bf16x8*)(kb + 32 * APITCH + ds * 32);
;             p0 = __builtin_amdgcn_mfma_f32_32x32x16_bf16(k0, qr[ds], p0, 0, 0, 0);
;             p1 = __builtin_amdgcn_mfma_f32_32x32x16_bf16(k1, qr[ds], p1, 0, 0, 0);
;         }
;         if (MODE == 0) {
;             const bool farl = (tok0 + 63 + 128 <= qtok0), farr = (tok0 - (qtok0 + 31) >= 128) && (tok0 + 64 <= LT);
;             if (farl || farr) { const float cb = farl ? mytab[0] : mytab[256];
; #pragma unroll
;                 for (int r = 0; r < 16; ++r) { p0[r] += cb; p1[r] += cb; } }
;             else {
; #pragma unroll
;                 for (int r = 0; r < 16; ++r) { const int tk0 = tok0 + crow(r, hi), tk1 = tk0 + 32;
;                     int i0 = tk0 - tq + 128; i0 = i0 < 0 ? 0 : (i0 > 256 ? 256 : i0); int i1 = tk1 - tq + 128; i1 = i1 < 0 ? 0 : (i1 > 256 ? 256 : i1);
;                     p0[r] = tk0 < LT ? p0[r] + mytab[i0] : NEGV; p1[r] = tk1 < LT ? p1[r] + mytab[i1] : NEGV; } }
;         } else if (MODE == 2) {
;           if (tok0 >= NMETA && tok0 + 64 <= LT) {
;             const LAS float* t2 = mytab2 + (tok0 - tq + 191 + 4 * hi);
; #pragma unroll
;             for (int r = 0; r < 16; ++r) { p0[r] += t2[(r & 3) + 8 * (r >> 2)]; p1[r] += t2[(r & 3) + 8 * (r >> 2) + 32]; }
;           } else
; #pragma unroll
;             for (int r = 0; r < 16; ++r) { const int tk0 = tok0 + crow(r, hi), tk1 = tk0 + 32; const int r0 = tk0 - tq, r1 = tk1 - tq;
;                 int i0 = r0 + 128; i0 = i0 < 0 ? 0 : (i0 > 256 ? 256 : i0); int i1 = r1 + 128; i1 = i1 < 0 ? 0 : (i1 > 256 ? 256 : i1);
;                 const bool v0 = (tk0 < NMETA || (r0 >= -128 && r0 <= 128)) && tk0 < LT, v1 = (tk1 < NMETA || (r1 >= -128 && r1 <= 128)) && tk1 < LT;
;                 p0[r] = v0 ? p0[r] + mytab[i0] : NEGV; p1[r] = v1 ? p1[r] + mytab[i1] : NEGV; }
.LBB0_1215:
	s_and_b64 vcc, exec, s[46:47]
	s_cbranch_vccnz .Lgqa2_t0fast
	s_mul_i32 s15, s35, 0x404
	s_add_i32 s34, s15, 0
	s_movk_i32 s15, 0x90
	v_mad_u32_u24 v3, v66, s15, 0
	v_lshlrev_b32_e32 v68, 4, v2
	v_add_u32_e32 v127, v3, v68
	v_lshlrev_b32_e32 v67, 2, v2
	ds_read_b128 v[18:21], v127 offset:4608
	ds_read_b128 v[2:5], v127
	ds_read_b128 v[36:39], v127 offset:32
	s_waitcnt lgkmcnt(1)
	v_mfma_f32_32x32x16_bf16 v[2:17], v[2:5], v[98:101], 0
	ds_read_b128 v[40:43], v127 offset:4640
	s_add_i32 s34, s34, 0x1b000
	v_mfma_f32_32x32x16_bf16 v[18:33], v[18:21], v[98:101], 0
	s_waitcnt lgkmcnt(1)
	v_mfma_f32_32x32x16_bf16 v[2:17], v[36:39], v[102:105], v[2:17]
	s_waitcnt lgkmcnt(0)
	v_mfma_f32_32x32x16_bf16 v[18:33], v[40:43], v[102:105], v[18:33]
	ds_read_b128 v[36:39], v127 offset:64
	ds_read_b128 v[40:43], v127 offset:4672
	s_waitcnt lgkmcnt(1)
	v_mfma_f32_32x32x16_bf16 v[2:17], v[36:39], v[106:109], v[2:17]
	s_waitcnt lgkmcnt(0)
	v_mfma_f32_32x32x16_bf16 v[18:33], v[40:43], v[106:109], v[18:33]
	ds_read_b128 v[36:39], v127 offset:96
	ds_read_b128 v[40:43], v127 offset:4704
	s_waitcnt lgkmcnt(1)
	v_mfma_f32_32x32x16_bf16 v[2:17], v[36:39], v[110:113], v[2:17]
	v_sub_u32_e32 v36, v67, v125
	v_add_u32_e32 v35, 0xa0, v36
	v_cmp_gt_u32_e32 vcc, s6, v35
	v_med3_i32 v35, v36, s87, v240
	v_lshl_add_u32 v35, v35, 2, s34
	ds_read_b32 v37, v35 offset:512
	v_mov_b32_e32 v35, 0xf149f2ca
	s_waitcnt lgkmcnt(1)
	v_mfma_f32_32x32x16_bf16 v[18:33], v[40:43], v[110:113], v[18:33]
	v_lshl_add_u32 v39, v36, 2, s34
	v_mov_b32_e32 v36, 0xf149f2ca
	s_and_saveexec_b64 s[28:29], vcc
	s_cbranch_execz .LBB0_1217
	ds_read_b32 v36, v39 offset:640
	s_waitcnt lgkmcnt(0)
	s_nop 5
	v_add_f32_e32 v36, v18, v36

; template <int MODE> __device__ __forceinline__ void attn_unit(const AttnP& P, int u, LAS char* lds, bool fill) {
;     ...
;         for (int ds = 0; ds < 4; ++ds) {
;     ...
;         float mx = p0[0];
; #pragma unroll
;         for (int r = 1; r < 16; ++r) mx = fmaxf(mx, p0[r]);
; #pragma unroll
;         for (int r = 0; r < 16; ++r) mx = fmaxf(mx, p1[r]);
;         { const auto rr = __builtin_amdgcn_permlane32_swap(__float_as_uint(mx), __float_as_uint(mx), false, false); mx = fmaxf(__uint_as_float(rr[0]), __uint_as_float(rr[1])); }
;         if (__any(mx > mrun + 8.0f)) {
;             const float mnew = fmaxf(mrun, mx); const float f = __builtin_amdgcn_exp2f(mrun - mnew); mrun = mnew; lrun *= f;
; #pragma unroll
;             for (int d = 0; d < ND; ++d)
; #pragma unroll
;                 for (int r = 0; r < 16; ++r) o[d][r] *= f;
;         }
;         float sacc = 0.f;
; #pragma unroll
;         for (int r = 0; r < 16; ++r) { p0[r] = __builtin_amdgcn_exp2f(p0[r] - mrun); p1[r] = __builtin_amdgcn_exp2f(p1[r] - mrun); sacc += p0[r] + p1[r]; }
;         lrun += sacc;
;         bf16x8 pf[4];
;         { u32x4 a;
;           a.x = cvtpk(p0[0], p0[1]); a.y = cvtpk(p0[2], p0[3]); a.z = cvtpk(p0[4], p0[5]); a.w = cvtpk(p0[6], p0[7]); pf[0] = __builtin_bit_cast(bf16x8, a);
;           a.x = cvtpk(p0[8], p0[9]); a.y = cvtpk(p0[10], p0[11]); a.z = cvtpk(p0[12], p0[13]); a.w = cvtpk(p0[14], p0[15]); pf[1] = __builtin_bit_cast(bf16x8, a);
;           a.x = cvtpk(p1[0], p1[1]); a.y = cvtpk(p1[2], p1[3]); a.z = cvtpk(p1[4], p1[5]); a.w = cvtpk(p1[6], p1[7]); pf[2] = __builtin_bit_cast(bf16x8, a);
;           a.x = cvtpk(p1[8], p1[9]); a.y = cvtpk(p1[10], p1[11]); a.z = cvtpk(p1[12], p1[13]); a.w = cvtpk(p1[14], p1[15]); pf[3] = __builtin_bit_cast(bf16x8, a); }
; #pragma unroll
;         for (int d = 0; d < ND; ++d) {
;             const int vslot = MODE == 0 ? 2 + (d >> 1) : MODE == 1 ? kslot + 1 : 1;
;             const LAS char* vb = lds + vslot * ASLOT + vrow * APITCH + (d & 1) * 64 + vcolb;
; #pragma unroll
;             for (int ks = 0; ks < 4; ++ks) {
;                 const s16x4 vl = vtr(vb + (16 * ks) * APITCH), vh = vtr(vb + (16 * ks + 8) * APITCH);
;                 const bf16x8 vf = (bf16x8){vl[0], vl[1], vl[2], vl[3], vh[0], vh[1], vh[2], vh[3]};
;                 o[d] = __builtin_amdgcn_mfma_f32_32x32x16_bf16(vf, pf[ks], o[d], 0, 0, 0);
;             }
;         }
.Lgqa2_t0fast:
	s_mul_i32 s15, s35, 0x404
	s_add_i32 s34, s15, 0x1b000
	s_movk_i32 s15, 0x90
	v_mad_u32_u24 v40, v66, s15, 0
	v_lshlrev_b32_e32 v68, 4, v2
	v_lshlrev_b32_e32 v67, 2, v2
	v_add_u32_e32 v127, v40, v68
	v_lshrrev_b32_e32 v41, 2, v34
	v_and_or_b32 v41, v41, 3, v67
	v_mul_u32_u24_e32 v42, 0x90, v41
	v_lshlrev_b32_e32 v43, 1, v34
	v_lshlrev_b32_e32 v44, 3, v34
	v_and_b32_e32 v43, 32, v43
	v_and_b32_e32 v44, 24, v44
	v_add3_u32 v45, 0, v43, v44
	v_add_u32_e32 v129, v45, v42
	v_mov_b32_e32 v88, s34
	ds_read_b32 v88, v88
	ds_read_b128 v[50:53], v127
	ds_read_b128 v[54:57], v127 offset:32
	ds_read_b128 v[58:61], v127 offset:64
	ds_read_b128 v[62:65], v127 offset:96
	ds_read_b64_tr_b16 v[84:85], v129 offset:9216
	ds_read_b64_tr_b16 v[86:87], v129 offset:10368
	ds_read_b64_tr_b16 v[74:75], v129 offset:9280
	ds_read_b64_tr_b16 v[76:77], v129 offset:10432
	s_waitcnt lgkmcnt(7)
	v_mfma_f32_32x32x16_bf16 v[34:49], v[50:53], v[98:101], 0
	s_waitcnt lgkmcnt(6)
	v_mfma_f32_32x32x16_bf16 v[34:49], v[54:57], v[102:105], v[34:49]
	s_waitcnt lgkmcnt(5)
	v_mfma_f32_32x32x16_bf16 v[34:49], v[58:61], v[106:109], v[34:49]
	s_waitcnt lgkmcnt(4)
	v_mfma_f32_32x32x16_bf16 v[34:49], v[62:65], v[110:113], v[34:49]
	s_nop 11
	v_add_f32_e32 v34, v34, v88
	v_add_f32_e32 v35, v35, v88
	v_add_f32_e32 v36, v36, v88
	v_add_f32_e32 v37, v37, v88
	v_add_f32_e32 v38, v38, v88
	v_add_f32_e32 v39, v39, v88
	v_add_f32_e32 v40, v40, v88
	v_add_f32_e32 v41, v41, v88
	v_max3_f32 v47, v34, v35, v36
	v_max3_f32 v47, v47, v37, v38
	v_max3_f32 v47, v47, v39, v40
	v_max_f32_e32 v47, v47, v41
	v_mov_b32_e32 v48, v47
	s_nop 1
	v_permlane32_swap_b32_e32 v47, v48
	v_max_f32_e32 v47, v47, v48
	v_max_f32_e32 v128, 0xf149f2ca, v47
	v_sub_f32_e32 v34, v34, v128
	v_sub_f32_e32 v35, v35, v128
	v_sub_f32_e32 v36, v36, v128
	v_sub_f32_e32 v37, v37, v128
	v_sub_f32_e32 v38, v38, v128
	v_sub_f32_e32 v39, v39, v128
	v_sub_f32_e32 v40, v40, v128
	v_sub_f32_e32 v41, v41, v128
	v_exp_f32_e32 v34, v34
	v_exp_f32_e32 v35, v35
	v_exp_f32_e32 v36, v36
	v_exp_f32_e32 v37, v37
	v_exp_f32_e32 v38, v38
	v_exp_f32_e32 v39, v39
	v_exp_f32_e32 v40, v40
	v_exp_f32_e32 v41, v41
	v_add_f32_e32 v130, v34, v35
	v_add_f32_e32 v130, v130, v36
	v_add_f32_e32 v130, v130, v37
	v_add_f32_e32 v130, v130, v38
	v_add_f32_e32 v130, v130, v39
	v_add_f32_e32 v130, v130, v40
	v_add_f32_e32 v130, v130, v41
	v_cvt_pk_bf16_f32 v80, v34, v35
	v_cvt_pk_bf16_f32 v81, v36, v37
	v_cvt_pk_bf16_f32 v82, v38, v39
	v_cvt_pk_bf16_f32 v83, v40, v41
	s_nop 1
	s_waitcnt lgkmcnt(0)
	v_mfma_f32_32x32x16_bf16 v[18:33], v[84:87], v[80:83], 0
	v_mfma_f32_32x32x16_bf16 v[2:17], v[74:77], v[80:83], 0
	s_andn2_b64 vcc, exec, s[0:1]
	s_cbranch_vccnz .LBB0_1339
.Lgqa2_t0done:
	s_add_i32 s15, s62, 0xffffff40
	s_and_b64 s[0:1], s[46:47], exec
	s_cselect_b32 s38, s15, 0
	s_mul_i32 s16, s35, 0x600
	s_lshl_b32 s0, s38, 2
	s_add_i32 s0, s0, s16
	v_add_u32_e32 v34, s0, v68
	v_lshlrev_b32_e32 v35, 2, v66
	s_lshl_b32 s0, s14, 1
	v_sub_u32_e32 v34, v34, v35
	s_and_b32 s0, s0, 0x80
	v_subrev_u32_e32 v34, s0, v34
	s_lshl_b32 s0, s44, 8
	v_subrev_u32_e32 v34, s0, v34
	v_readlane_b32 s0, v255, 24
	s_add_i32 s43, s43, s45
	v_add_u32_e32 v132, s38, v67
	v_add_u32_e32 v131, s0, v34
	v_add_u32_e32 v34, s43, v66
	s_mov_b32 s35, 0
	s_mov_b32 s39, 1
	s_sub_i32 s14, s62, 64
	v_sub_u32_e32 v133, v132, v34
	s_branch .LBB0_1266
